# forgetting-attention main loop: lane-local folded rescale test; cross-half max exchange, new max, rescale factor and O rescale on an out-of-line rare path
# baseline (speedup 1.0000x reference)
.LBB0_1171:
	v_max_f32_e32 v2, v96, v97
	v_max3_f32 v2, v2, v98, v99
	v_max3_f32 v2, v2, v100, v101
	v_max3_f32 v2, v2, v102, v103
	v_max3_f32 v2, v2, v104, v105
	v_max3_f32 v2, v2, v106, v107
	v_max3_f32 v2, v2, v108, v109
	v_max3_f32 v2, v2, v110, v111
	v_max3_f32 v2, v2, v80, v81
	v_max3_f32 v2, v2, v82, v83
	v_max3_f32 v2, v2, v84, v85
	v_max3_f32 v2, v2, v86, v87
	v_max3_f32 v2, v2, v88, v89
	v_max3_f32 v2, v2, v90, v91
	v_max3_f32 v2, v2, v92, v93
	v_max3_f32 v2, v2, v94, v95
	v_sub_f32_e32 v4, v2, v201
	v_cmp_ge_f32_e32 vcc, 0x42b504f3, v4
	s_cmp_eq_u64 vcc, exec
	s_cbranch_scc0 .Lattn1_slowA
	v_mov_b32_e32 v4, 1.0
	v_mov_b32_e32 v2, v201
.LBB0_1175:
	s_waitcnt vmcnt(5) lgkmcnt(0)
	s_barrier
	s_add_i32 s8, s61, s90
	s_mov_b32 s9, m0
	s_mov_b32 m0, s8
	s_nop 0
	global_load_lds_dwordx4 v183, s[62:63]
	s_mov_b32 m0, s9
	s_addk_i32 s8, 0x400
	s_mov_b32 s9, m0
	s_mov_b32 m0, s8
	s_nop 0
	global_load_lds_dwordx4 v184, s[62:63]
	s_mov_b32 m0, s9
	s_ashr_i32 s8, s61, 6
	s_cmp_lg_u32 0, -1
	s_cselect_b32 s9, 0, 0
	s_add_i32 s8, s9, s8
	s_add_i32 s8, s8, 0x18800
	s_mov_b32 s9, m0
	s_mov_b32 m0, s8
	s_nop 0
	global_load_lds_dword v185, s[0:1]
	s_mov_b32 m0, s9
	s_add_u32 s8, s56, s66
	s_addc_u32 s9, s57, s67
	s_add_i32 s65, s53, s83
	s_mov_b32 s66, m0
	s_mov_b32 m0, s65
	s_nop 0
	global_load_lds_dwordx4 v187, s[8:9]
	s_mov_b32 m0, s66
	s_addk_i32 s65, 0x400
	s_mov_b32 s66, m0
	s_mov_b32 m0, s65
	s_nop 0
	global_load_lds_dwordx4 v186, s[8:9]
	s_mov_b32 m0, s66
	v_mul_f32_e32 v5, 0xbe0293ee, v2
	v_fmamk_f32 v6, v96, 0x3e0293ee, v5
	v_fmamk_f32 v7, v97, 0x3e0293ee, v5
	v_fmamk_f32 v8, v98, 0x3e0293ee, v5
	v_fmamk_f32 v9, v99, 0x3e0293ee, v5
	v_fmamk_f32 v10, v100, 0x3e0293ee, v5
	v_fmamk_f32 v11, v101, 0x3e0293ee, v5
	v_fmamk_f32 v12, v102, 0x3e0293ee, v5
	v_fmamk_f32 v13, v103, 0x3e0293ee, v5
	v_fmamk_f32 v14, v104, 0x3e0293ee, v5
	v_fmamk_f32 v15, v105, 0x3e0293ee, v5
	v_fmamk_f32 v96, v106, 0x3e0293ee, v5
	v_fmamk_f32 v97, v107, 0x3e0293ee, v5
	v_fmamk_f32 v98, v108, 0x3e0293ee, v5
	v_fmamk_f32 v99, v109, 0x3e0293ee, v5
	v_fmamk_f32 v100, v110, 0x3e0293ee, v5
	v_fmamk_f32 v101, v111, 0x3e0293ee, v5
	v_fmamk_f32 v112, v80, 0x3e0293ee, v5
	v_fmamk_f32 v113, v81, 0x3e0293ee, v5
	v_fmamk_f32 v114, v82, 0x3e0293ee, v5
	v_fmamk_f32 v115, v83, 0x3e0293ee, v5
	v_fmamk_f32 v116, v84, 0x3e0293ee, v5
	v_fmamk_f32 v117, v85, 0x3e0293ee, v5
	v_fmamk_f32 v118, v86, 0x3e0293ee, v5
	v_fmamk_f32 v119, v87, 0x3e0293ee, v5
	v_fmamk_f32 v120, v88, 0x3e0293ee, v5
	v_fmamk_f32 v121, v89, 0x3e0293ee, v5
	v_fmamk_f32 v122, v90, 0x3e0293ee, v5
	v_fmamk_f32 v123, v91, 0x3e0293ee, v5
	v_fmamk_f32 v124, v92, 0x3e0293ee, v5
	v_fmamk_f32 v125, v93, 0x3e0293ee, v5
	v_fmamk_f32 v126, v94, 0x3e0293ee, v5
	v_fmac_f32_e32 v5, 0x3e0293ee, v95
	v_exp_f32_e32 v127, v6
	v_exp_f32_e32 v131, v7
	v_exp_f32_e32 v132, v8
	v_exp_f32_e32 v133, v9
	v_exp_f32_e32 v10, v10
	v_exp_f32_e32 v11, v11
	v_exp_f32_e32 v12, v12
	v_exp_f32_e32 v13, v13
	v_exp_f32_e32 v14, v14
	v_exp_f32_e32 v15, v15
	v_exp_f32_e32 v134, v96
	v_exp_f32_e32 v135, v97
	v_exp_f32_e32 v136, v98
	v_exp_f32_e32 v137, v99
	v_exp_f32_e32 v138, v100
	v_exp_f32_e32 v139, v101
	s_ashr_i32 s8, s68, 8
	v_lshl_add_u32 v6, s8, 2, v128
	ds_read_b128 v[96:99], v6
	ds_read_b128 v[100:103], v6 offset:32
	ds_read_b128 v[80:83], v6 offset:128
	ds_read_b128 v[84:87], v6 offset:160
	ds_read_b128 v[104:107], v6 offset:64
	ds_read_b128 v[108:111], v6 offset:96
	ds_read_b128 v[88:91], v6 offset:192
	ds_read_b128 v[92:95], v6 offset:224
	s_add_i32 s8, s68, 0
	v_add3_u32 v140, s8, v197, v196
	v_add3_u32 v141, s8, v198, v196
	v_add3_u32 v142, s8, v199, v196
	v_add3_u32 v143, s8, v200, v196
	s_setprio 1
	ds_read_b128 v[6:9], v140 offset:49152
	ds_read_b128 v[220:223], v140 offset:57344
	ds_read_b128 v[224:227], v141 offset:49152
	ds_read_b128 v[228:231], v141 offset:57344
	ds_read_b128 v[232:235], v142 offset:49152
	s_waitcnt lgkmcnt(4)
	v_mfma_f32_32x32x16_bf16 v[96:111], v[6:9], v[172:175], v[96:111]
	ds_read_b128 v[6:9], v142 offset:57344
	s_waitcnt lgkmcnt(4)
	v_mfma_f32_32x32x16_bf16 v[80:95], v[220:223], v[172:175], v[80:95]
	ds_read_b128 v[220:223], v143 offset:49152
	s_waitcnt lgkmcnt(4)
	v_mfma_f32_32x32x16_bf16 v[96:111], v[224:227], v[168:171], v[96:111]
	ds_read_b128 v[224:227], v143 offset:57344
	s_waitcnt lgkmcnt(4)
	v_mfma_f32_32x32x16_bf16 v[80:95], v[228:231], v[168:171], v[80:95]
	ds_read_b128 v[228:231], v140 offset:49280
	s_waitcnt lgkmcnt(4)
	v_mfma_f32_32x32x16_bf16 v[96:111], v[232:235], v[164:167], v[96:111]
	ds_read_b128 v[232:235], v140 offset:57472
	s_waitcnt lgkmcnt(4)
	v_mfma_f32_32x32x16_bf16 v[80:95], v[6:9], v[164:167], v[80:95]
	ds_read_b128 v[6:9], v141 offset:49280
	s_waitcnt lgkmcnt(4)
	v_mfma_f32_32x32x16_bf16 v[96:111], v[220:223], v[160:163], v[96:111]
	ds_read_b128 v[220:223], v141 offset:57472
	s_waitcnt lgkmcnt(4)
	v_mfma_f32_32x32x16_bf16 v[80:95], v[224:227], v[160:163], v[80:95]
	ds_read_b128 v[224:227], v142 offset:49280
	s_waitcnt lgkmcnt(4)
	v_mfma_f32_32x32x16_bf16 v[96:111], v[228:231], v[156:159], v[96:111]
	ds_read_b128 v[228:231], v142 offset:57472
	s_waitcnt lgkmcnt(4)
	v_mfma_f32_32x32x16_bf16 v[80:95], v[232:235], v[156:159], v[80:95]
	ds_read_b128 v[232:235], v143 offset:49280
	s_waitcnt lgkmcnt(4)
	v_mfma_f32_32x32x16_bf16 v[96:111], v[6:9], v[152:155], v[96:111]
	ds_read_b128 v[6:9], v143 offset:57472
	s_waitcnt lgkmcnt(4)
	v_mfma_f32_32x32x16_bf16 v[80:95], v[220:223], v[152:155], v[80:95]
	s_waitcnt lgkmcnt(3)
	v_mfma_f32_32x32x16_bf16 v[96:111], v[224:227], v[148:151], v[96:111]
	s_waitcnt lgkmcnt(2)
	v_mfma_f32_32x32x16_bf16 v[80:95], v[228:231], v[148:151], v[80:95]
	s_waitcnt lgkmcnt(1)
	v_mfma_f32_32x32x16_bf16 v[96:111], v[232:235], v[144:147], v[96:111]
	s_waitcnt lgkmcnt(0)
	v_mfma_f32_32x32x16_bf16 v[80:95], v[6:9], v[144:147], v[80:95]
	s_setprio 0
	v_exp_f32_e32 v7, v112
	v_exp_f32_e32 v112, v113
	v_exp_f32_e32 v113, v114
	v_exp_f32_e32 v114, v115
	v_exp_f32_e32 v115, v116
	v_exp_f32_e32 v116, v117
	v_exp_f32_e32 v117, v118
	v_exp_f32_e32 v118, v119
	v_exp_f32_e32 v119, v120
	v_exp_f32_e32 v120, v121
	v_exp_f32_e32 v121, v122
	v_exp_f32_e32 v122, v123
	v_exp_f32_e32 v123, v124
	v_exp_f32_e32 v124, v125
	v_exp_f32_e32 v125, v126
	v_exp_f32_e32 v126, v5
	v_add_f32_e32 v5, 0, v127
	v_add_f32_e32 v5, v131, v5
	v_add_f32_e32 v5, v132, v5
	v_add_f32_e32 v5, v133, v5
	v_add_f32_e32 v5, v10, v5
	v_add_f32_e32 v5, v11, v5
	v_add_f32_e32 v5, v12, v5
	v_add_f32_e32 v5, v13, v5
	v_add_f32_e32 v5, v14, v5
	v_add_f32_e32 v5, v15, v5
	v_add_f32_e32 v5, v134, v5
	v_add_f32_e32 v5, v135, v5
	v_add_f32_e32 v5, v136, v5
	v_add_f32_e32 v5, v137, v5
	v_add_f32_e32 v5, v138, v5
	v_add_f32_e32 v5, v139, v5
	v_add_f32_e32 v5, v7, v5
	v_add_f32_e32 v5, v112, v5
	v_add_f32_e32 v5, v113, v5
	v_add_f32_e32 v5, v114, v5
	v_add_f32_e32 v5, v115, v5
	v_add_f32_e32 v5, v116, v5
	v_add_f32_e32 v5, v117, v5
	v_add_f32_e32 v5, v118, v5
	v_add_f32_e32 v5, v119, v5
	v_add_f32_e32 v5, v120, v5
	v_add_f32_e32 v5, v121, v5
	v_add_f32_e32 v5, v122, v5
	v_add_f32_e32 v5, v123, v5
	v_add_f32_e32 v5, v124, v5
	v_add_f32_e32 v5, v125, v5
	v_add_f32_e32 v5, v126, v5
	v_mov_b32_e32 v6, v5
	s_nop 1
	v_permlane32_swap_b32_e32 v5, v6
	v_cvt_pk_bf16_f32 v8, v127, v131
	v_cvt_pk_bf16_f32 v9, v132, v133
	v_cvt_pk_bf16_f32 v10, v10, v11
	v_cvt_pk_bf16_f32 v11, v12, v13
	v_cvt_pk_bf16_f32 v12, v14, v15
	v_cvt_pk_bf16_f32 v13, v134, v135
	v_cvt_pk_bf16_f32 v14, v136, v137
	v_cvt_pk_bf16_f32 v15, v138, v139
	v_cvt_pk_bf16_f32 v112, v7, v112
	v_cvt_pk_bf16_f32 v113, v113, v114
	v_cvt_pk_bf16_f32 v114, v115, v116
	v_cvt_pk_bf16_f32 v115, v117, v118
	v_cvt_pk_bf16_f32 v116, v119, v120
	v_cvt_pk_bf16_f32 v117, v121, v122
	v_cvt_pk_bf16_f32 v118, v123, v124
	v_cvt_pk_bf16_f32 v119, v125, v126
	s_nop 0
	v_add_u32_e32 v7, s61, v193
	ds_read_b64_tr_b16 v[120:121], v7 offset:0
	ds_read_b64_tr_b16 v[122:123], v7 offset:0x800
	ds_read_b64_tr_b16 v[124:125], v7 offset:0x1000
	ds_read_b64_tr_b16 v[126:127], v7 offset:0x1800
	ds_read_b64_tr_b16 v[132:133], v7 offset:0x2000
	ds_read_b64_tr_b16 v[134:135], v7 offset:0x2800
	ds_read_b64_tr_b16 v[136:137], v7 offset:0x3000
	ds_read_b64_tr_b16 v[138:139], v7 offset:0x3800
	s_waitcnt lgkmcnt(6)
	s_nop 0
	v_mfma_f32_32x32x16_bf16 v[16:31], v[8:11], v[120:123], v[16:31]
	ds_read_b64_tr_b16 v[120:121], v7 offset:0x200
	ds_read_b64_tr_b16 v[122:123], v7 offset:0xa00
	s_waitcnt lgkmcnt(6)
	v_mfma_f32_32x32x16_bf16 v[16:31], v[12:15], v[124:127], v[16:31]
	ds_read_b64_tr_b16 v[124:125], v7 offset:0x1200
	ds_read_b64_tr_b16 v[126:127], v7 offset:0x1a00
	s_waitcnt lgkmcnt(6)
	v_mfma_f32_32x32x16_bf16 v[16:31], v[112:115], v[132:135], v[16:31]
	ds_read_b64_tr_b16 v[132:133], v7 offset:0x2200
	ds_read_b64_tr_b16 v[134:135], v7 offset:0x2a00
	s_waitcnt lgkmcnt(6)
	v_mfma_f32_32x32x16_bf16 v[16:31], v[116:119], v[136:139], v[16:31]
	ds_read_b64_tr_b16 v[136:137], v7 offset:0x3200
	ds_read_b64_tr_b16 v[138:139], v7 offset:0x3a00
	s_waitcnt lgkmcnt(6)
	v_mfma_f32_32x32x16_bf16 v[48:63], v[8:11], v[120:123], v[48:63]
	ds_read_b64_tr_b16 v[120:121], v7 offset:0x400
	ds_read_b64_tr_b16 v[122:123], v7 offset:0xc00
	s_waitcnt lgkmcnt(6)
	v_mfma_f32_32x32x16_bf16 v[48:63], v[12:15], v[124:127], v[48:63]
	ds_read_b64_tr_b16 v[124:125], v7 offset:0x1400
	ds_read_b64_tr_b16 v[126:127], v7 offset:0x1c00
	s_waitcnt lgkmcnt(6)
	v_mfma_f32_32x32x16_bf16 v[48:63], v[112:115], v[132:135], v[48:63]
	ds_read_b64_tr_b16 v[132:133], v7 offset:0x2400
	ds_read_b64_tr_b16 v[134:135], v7 offset:0x2c00
	s_waitcnt lgkmcnt(6)
	v_mfma_f32_32x32x16_bf16 v[48:63], v[116:119], v[136:139], v[48:63]
	ds_read_b64_tr_b16 v[136:137], v7 offset:0x3400
	ds_read_b64_tr_b16 v[138:139], v7 offset:0x3c00
	s_waitcnt lgkmcnt(6)
	v_mfma_f32_32x32x16_bf16 v[64:79], v[8:11], v[120:123], v[64:79]
	ds_read_b64_tr_b16 v[120:121], v7 offset:0x600
	ds_read_b64_tr_b16 v[122:123], v7 offset:0xe00
	s_waitcnt lgkmcnt(6)
	v_mfma_f32_32x32x16_bf16 v[64:79], v[12:15], v[124:127], v[64:79]
	ds_read_b64_tr_b16 v[124:125], v7 offset:0x1600
	ds_read_b64_tr_b16 v[126:127], v7 offset:0x1e00
	s_waitcnt lgkmcnt(6)
	v_mfma_f32_32x32x16_bf16 v[64:79], v[112:115], v[132:135], v[64:79]
	ds_read_b64_tr_b16 v[132:133], v7 offset:0x2600
	ds_read_b64_tr_b16 v[134:135], v7 offset:0x2e00
	s_waitcnt lgkmcnt(6)
	v_mfma_f32_32x32x16_bf16 v[64:79], v[116:119], v[136:139], v[64:79]
	ds_read_b64_tr_b16 v[136:137], v7 offset:0x3600
	ds_read_b64_tr_b16 v[138:139], v7 offset:0x3e00
	s_waitcnt lgkmcnt(6)
	v_mfma_f32_32x32x16_bf16 v[32:47], v[8:11], v[120:123], v[32:47]
	s_cmp_le_i32 s91, s69
	s_waitcnt lgkmcnt(4)
	v_mfma_f32_32x32x16_bf16 v[32:47], v[12:15], v[124:127], v[32:47]
	s_waitcnt lgkmcnt(2)
	v_mfma_f32_32x32x16_bf16 v[32:47], v[112:115], v[132:135], v[32:47]
	s_waitcnt lgkmcnt(0)
	v_mfma_f32_32x32x16_bf16 v[32:47], v[116:119], v[136:139], v[32:47]
	s_cbranch_scc1 .LBB0_1177
	v_add_u32_e32 v7, 0x4000007b, v130
	v_cmp_gt_u32_e32 vcc, 2.0, v7
	v_add_u32_e32 v7, 0x5b, v130
	s_nop 0
	v_cndmask_b32_e32 v96, v179, v96, vcc
	v_cmp_lt_u32_e32 vcc, s96, v7
	v_add_u32_e32 v7, 0x7a, v130
	s_nop 0
	v_cndmask_b32_e32 v80, v179, v80, vcc
	v_cmp_lt_u32_e32 vcc, s96, v7
	v_add_u32_e32 v7, 0x5a, v130
	s_nop 0
	v_cndmask_b32_e32 v97, v179, v97, vcc
	v_cmp_lt_u32_e32 vcc, s96, v7
	v_add_u32_e32 v7, 0x79, v130
	s_nop 0
	v_cndmask_b32_e32 v81, v179, v81, vcc
	v_cmp_lt_u32_e32 vcc, s96, v7
	v_add_u32_e32 v7, 0x59, v130
	s_nop 0
	v_cndmask_b32_e32 v98, v179, v98, vcc
	v_cmp_lt_u32_e32 vcc, s96, v7
	v_add_u32_e32 v7, 0x78, v130
	s_nop 0
	v_cndmask_b32_e32 v82, v179, v82, vcc
	v_cmp_lt_u32_e32 vcc, s96, v7
	v_add_u32_e32 v7, 0x58, v130
	s_nop 0
	v_cndmask_b32_e32 v99, v179, v99, vcc
	v_cmp_lt_u32_e32 vcc, s96, v7
	v_add_u32_e32 v7, 0x73, v130
	s_nop 0
	v_cndmask_b32_e32 v83, v179, v83, vcc
	v_cmp_lt_u32_e32 vcc, s96, v7
	v_add_u32_e32 v7, 0x53, v130
	s_nop 0
	v_cndmask_b32_e32 v100, v179, v100, vcc
	v_cmp_lt_u32_e32 vcc, s96, v7
	v_add_u32_e32 v7, 0x72, v130
	s_nop 0
	v_cndmask_b32_e32 v84, v179, v84, vcc
	v_cmp_lt_u32_e32 vcc, s96, v7
	v_add_u32_e32 v7, 0x52, v130
	s_nop 0
	v_cndmask_b32_e32 v101, v179, v101, vcc
	v_cmp_lt_u32_e32 vcc, s96, v7
	v_add_u32_e32 v7, 0x71, v130
	s_nop 0
	v_cndmask_b32_e32 v85, v179, v85, vcc
	v_cmp_lt_u32_e32 vcc, s96, v7
	v_add_u32_e32 v7, 0x51, v130
	s_nop 0
	v_cndmask_b32_e32 v102, v179, v102, vcc
	v_cmp_lt_u32_e32 vcc, s96, v7
	v_add_u32_e32 v7, 0x70, v130
	s_nop 0
	v_cndmask_b32_e32 v86, v179, v86, vcc
	v_cmp_lt_u32_e32 vcc, s96, v7
	v_add_u32_e32 v7, 0x50, v130
	s_nop 0
	v_cndmask_b32_e32 v103, v179, v103, vcc
	v_cmp_lt_u32_e32 vcc, s96, v7
	v_add_u32_e32 v7, 0x6b, v130
	s_nop 0
	v_cndmask_b32_e32 v87, v179, v87, vcc
	v_cmp_lt_u32_e32 vcc, s96, v7
	v_add_u32_e32 v7, 0x4b, v130
	s_nop 0
	v_cndmask_b32_e32 v104, v179, v104, vcc
	v_cmp_lt_u32_e32 vcc, s96, v7
	v_add_u32_e32 v7, 0x6a, v130
	s_nop 0
	v_cndmask_b32_e32 v88, v179, v88, vcc
	v_cmp_lt_u32_e32 vcc, s96, v7
	v_add_u32_e32 v7, 0x4a, v130
	s_nop 0
	v_cndmask_b32_e32 v105, v179, v105, vcc
	v_cmp_lt_u32_e32 vcc, s96, v7
	v_add_u32_e32 v7, 0x69, v130
	s_nop 0
	v_cndmask_b32_e32 v89, v179, v89, vcc
	v_cmp_lt_u32_e32 vcc, s96, v7
	v_add_u32_e32 v7, 0x49, v130
	s_nop 0
	v_cndmask_b32_e32 v106, v179, v106, vcc
	v_cmp_lt_u32_e32 vcc, s96, v7
	v_add_u32_e32 v7, 0x68, v130
	s_nop 0
	v_cndmask_b32_e32 v90, v179, v90, vcc
	v_cmp_lt_u32_e32 vcc, s96, v7
	v_add_u32_e32 v7, 0x48, v130
	s_nop 0
	v_cndmask_b32_e32 v107, v179, v107, vcc
	v_cmp_lt_u32_e32 vcc, s96, v7
	v_add_u32_e32 v7, 0x63, v130
	s_nop 0
	v_cndmask_b32_e32 v91, v179, v91, vcc
	v_cmp_lt_u32_e32 vcc, s96, v7
	v_add_u32_e32 v7, 0x43, v130
	s_nop 0
	v_cndmask_b32_e32 v108, v179, v108, vcc
	v_cmp_lt_u32_e32 vcc, s96, v7
	v_add_u32_e32 v7, 0x62, v130
	s_nop 0
	v_cndmask_b32_e32 v92, v179, v92, vcc
	v_cmp_lt_u32_e32 vcc, s96, v7
	v_add_u32_e32 v7, 0x42, v130
	s_nop 0
	v_cndmask_b32_e32 v109, v179, v109, vcc
	v_cmp_lt_u32_e32 vcc, s96, v7
	v_add_u32_e32 v7, 0x61, v130
	s_nop 0
	v_cndmask_b32_e32 v93, v179, v93, vcc
	v_cmp_lt_u32_e32 vcc, s96, v7
	v_add_u32_e32 v7, 0x41, v130
	s_nop 0
	v_cndmask_b32_e32 v110, v179, v110, vcc
	v_cmp_lt_u32_e32 vcc, s96, v7
	v_add_u32_e32 v7, 0x60, v130
	s_nop 0
	v_cndmask_b32_e32 v94, v179, v94, vcc
	v_cmp_lt_u32_e32 vcc, s96, v7
	v_add_u32_e32 v7, 64, v130
	s_nop 0
	v_cndmask_b32_e32 v111, v179, v111, vcc
	v_cmp_lt_u32_e32 vcc, s96, v7
	s_nop 1
	v_cndmask_b32_e32 v95, v179, v95, vcc
.LBB0_1177:
	v_max_f32_e32 v7, v96, v97
	v_max3_f32 v7, v7, v98, v99
	v_max3_f32 v7, v7, v100, v101
	v_max3_f32 v7, v7, v102, v103
	v_max3_f32 v7, v7, v104, v105
	v_max3_f32 v7, v7, v106, v107
	v_max3_f32 v7, v7, v108, v109
	v_max3_f32 v7, v7, v110, v111
	v_max3_f32 v7, v7, v80, v81
	v_max3_f32 v7, v7, v82, v83
	v_max3_f32 v7, v7, v84, v85
	v_max3_f32 v7, v7, v86, v87
	v_max3_f32 v7, v7, v88, v89
	v_max3_f32 v7, v7, v90, v91
	v_max3_f32 v7, v7, v92, v93
	v_max3_f32 v7, v7, v94, v95
	v_sub_f32_e32 v8, v7, v2
	v_cmp_ge_f32_e32 vcc, 0x42b504f3, v8
	s_cmp_eq_u64 vcc, exec
	s_cbranch_scc0 .Lattn1_slowB
	v_mov_b32_e32 v7, 1.0
	v_mov_b32_e32 v201, v2
.LBB0_1181:
	v_mul_f32_e32 v2, 0xbe0293ee, v201
	s_addk_i32 s91, 0xff80
	s_add_i32 s64, s64, -2
	s_add_i32 s8, s89, 2
	v_fmamk_f32 v8, v96, 0x3e0293ee, v2
	v_fmamk_f32 v9, v97, 0x3e0293ee, v2
	v_fmamk_f32 v10, v98, 0x3e0293ee, v2
	v_fmamk_f32 v11, v99, 0x3e0293ee, v2
	v_fmamk_f32 v12, v100, 0x3e0293ee, v2
	v_fmamk_f32 v13, v101, 0x3e0293ee, v2
	v_fmamk_f32 v14, v102, 0x3e0293ee, v2
	v_fmamk_f32 v15, v103, 0x3e0293ee, v2
	v_fmamk_f32 v96, v104, 0x3e0293ee, v2
	v_fmamk_f32 v97, v105, 0x3e0293ee, v2
	v_fmamk_f32 v98, v106, 0x3e0293ee, v2
	v_fmamk_f32 v99, v107, 0x3e0293ee, v2
	v_fmamk_f32 v100, v108, 0x3e0293ee, v2
	v_fmamk_f32 v101, v109, 0x3e0293ee, v2
	v_fmamk_f32 v102, v110, 0x3e0293ee, v2
	v_fmamk_f32 v103, v111, 0x3e0293ee, v2
	s_add_u32 s0, s0, 0xfffffe00
	v_exp_f32_e32 v215, v8
	v_exp_f32_e32 v217, v9
	v_exp_f32_e32 v213, v10
	v_exp_f32_e32 v216, v11
	v_exp_f32_e32 v211, v12
	v_exp_f32_e32 v214, v13
	v_exp_f32_e32 v210, v14
	v_exp_f32_e32 v212, v15
	v_exp_f32_e32 v205, v96
	v_exp_f32_e32 v208, v97
	v_exp_f32_e32 v203, v98
	v_exp_f32_e32 v206, v99
	v_exp_f32_e32 v202, v100
	v_exp_f32_e32 v209, v101
	v_exp_f32_e32 v204, v102
	v_exp_f32_e32 v207, v103
	s_addc_u32 s1, s1, -1
	v_add_f32_e32 v1, v1, v3
	s_waitcnt vmcnt(5) lgkmcnt(0)
	s_barrier
	s_add_u32 s62, s62, 0xffff8000
	v_fmac_f32_e32 v1, v129, v194
	v_add_f32_e32 v194, v5, v6
	s_addc_u32 s63, s63, -1
	v_pk_fma_f32 v[112:113], v[94:95], s[16:17], v[2:3] op_sel_hi:[1,0,0]
	v_pk_fma_f32 v[114:115], v[92:93], s[16:17], v[2:3] op_sel_hi:[1,0,0]
	v_pk_fma_f32 v[116:117], v[90:91], s[16:17], v[2:3] op_sel_hi:[1,0,0]
	v_pk_fma_f32 v[118:119], v[88:89], s[16:17], v[2:3] op_sel_hi:[1,0,0]
	v_pk_fma_f32 v[120:121], v[86:87], s[16:17], v[2:3] op_sel_hi:[1,0,0]
	v_pk_fma_f32 v[122:123], v[84:85], s[16:17], v[2:3] op_sel_hi:[1,0,0]
	v_pk_fma_f32 v[124:125], v[82:83], s[16:17], v[2:3] op_sel_hi:[1,0,0]
	v_pk_fma_f32 v[126:127], v[80:81], s[16:17], v[2:3] op_sel_hi:[1,0,0]
	v_fmac_f32_e32 v194, v1, v4
	s_cmp_ge_i32 s8, s87
	v_add_u32_e32 v130, 0x80, v130
	s_cbranch_scc1 .LBB0_1185
	s_mov_b32 s89, s8
	s_mov_b32 s65, s68
	s_mov_b32 s68, s61
	v_mov_b32_e32 v129, v7
	s_branch .LBB0_1169
.Lattn1_slowA:
	v_mov_b32_e32 v4, v2
	s_nop 1
	v_permlane32_swap_b32_e32 v2, v4
	v_max_f32_e32 v2, v2, v4
	v_max_f32_e32 v2, v201, v2
	v_sub_f32_e32 v4, v201, v2
	v_mul_f32_e32 v4, 0x3e0293ee, v4
	v_exp_f32_e32 v4, v4
	s_nop 0
	v_cmp_gt_f32_e32 vcc, 1.0, v4
	s_cbranch_vccz .LBB0_1175
	s_and_saveexec_b64 s[70:71], s[6:7]
	ds_write_b32 v191, v4 offset:128
	s_or_b64 exec, exec, s[70:71]
	s_waitcnt lgkmcnt(0)
	ds_read_b128 v[6:9], v190 offset:224
	ds_read_b128 v[10:13], v190 offset:192
	ds_read_b128 v[112:115], v190 offset:160
	ds_read_b128 v[116:119], v190 offset:128
	s_waitcnt lgkmcnt(3)
	v_pk_mul_f32 v[30:31], v[30:31], v[8:9]
	s_waitcnt lgkmcnt(2)
	v_pk_mul_f32 v[26:27], v[26:27], v[12:13]
	s_waitcnt lgkmcnt(1)
	v_pk_mul_f32 v[22:23], v[22:23], v[114:115]
	s_waitcnt lgkmcnt(0)
	v_pk_mul_f32 v[18:19], v[18:19], v[118:119]
	v_pk_mul_f32 v[28:29], v[28:29], v[6:7]
	v_pk_mul_f32 v[24:25], v[24:25], v[10:11]
	v_pk_mul_f32 v[20:21], v[20:21], v[112:113]
	v_pk_mul_f32 v[16:17], v[16:17], v[116:117]
	v_pk_mul_f32 v[62:63], v[62:63], v[8:9]
	v_pk_mul_f32 v[58:59], v[58:59], v[12:13]
	v_pk_mul_f32 v[54:55], v[54:55], v[114:115]
	v_pk_mul_f32 v[50:51], v[50:51], v[118:119]
	v_pk_mul_f32 v[60:61], v[60:61], v[6:7]
	v_pk_mul_f32 v[56:57], v[56:57], v[10:11]
	v_pk_mul_f32 v[52:53], v[52:53], v[112:113]
	v_pk_mul_f32 v[48:49], v[48:49], v[116:117]
	v_pk_mul_f32 v[78:79], v[78:79], v[8:9]
	v_pk_mul_f32 v[74:75], v[74:75], v[12:13]
	v_pk_mul_f32 v[70:71], v[70:71], v[114:115]
	v_pk_mul_f32 v[66:67], v[66:67], v[118:119]
	v_pk_mul_f32 v[76:77], v[76:77], v[6:7]
	v_pk_mul_f32 v[72:73], v[72:73], v[10:11]
	v_pk_mul_f32 v[68:69], v[68:69], v[112:113]
	v_pk_mul_f32 v[64:65], v[64:65], v[116:117]
	v_pk_mul_f32 v[46:47], v[46:47], v[8:9]
	v_pk_mul_f32 v[42:43], v[42:43], v[12:13]
	v_pk_mul_f32 v[38:39], v[38:39], v[114:115]
	v_pk_mul_f32 v[34:35], v[34:35], v[118:119]
	v_pk_mul_f32 v[44:45], v[44:45], v[6:7]
	v_pk_mul_f32 v[40:41], v[40:41], v[10:11]
	v_pk_mul_f32 v[36:37], v[36:37], v[112:113]
	v_pk_mul_f32 v[32:33], v[32:33], v[116:117]
	s_branch .LBB0_1175
.Lattn1_slowB:
	v_mov_b32_e32 v8, v7
	s_nop 1
	v_permlane32_swap_b32_e32 v7, v8
	v_max_f32_e32 v7, v7, v8
	v_max_f32_e32 v8, v2, v7
	v_sub_f32_e32 v7, v2, v8
	v_mul_f32_e32 v7, 0x3e0293ee, v7
	v_exp_f32_e32 v7, v7
	v_mov_b32_e32 v201, v8
	v_cmp_gt_f32_e32 vcc, 1.0, v7
	s_cbranch_vccz .LBB0_1181
	s_and_saveexec_b64 s[66:67], s[6:7]
	ds_write_b32 v191, v7 offset:128
	s_or_b64 exec, exec, s[66:67]
	s_waitcnt lgkmcnt(0)
	ds_read_b128 v[10:13], v190 offset:224
	ds_read_b128 v[112:115], v190 offset:192
	ds_read_b128 v[116:119], v190 offset:160
	ds_read_b128 v[120:123], v190 offset:128
	s_waitcnt lgkmcnt(3)
	v_pk_mul_f32 v[30:31], v[30:31], v[12:13]
	s_waitcnt lgkmcnt(2)
	v_pk_mul_f32 v[26:27], v[26:27], v[114:115]
	s_waitcnt lgkmcnt(1)
	v_pk_mul_f32 v[22:23], v[22:23], v[118:119]
	s_waitcnt lgkmcnt(0)
	v_pk_mul_f32 v[18:19], v[18:19], v[122:123]
	v_pk_mul_f32 v[28:29], v[28:29], v[10:11]
	v_pk_mul_f32 v[24:25], v[24:25], v[112:113]
	v_pk_mul_f32 v[20:21], v[20:21], v[116:117]
	v_pk_mul_f32 v[16:17], v[16:17], v[120:121]
	v_pk_mul_f32 v[62:63], v[62:63], v[12:13]
	v_pk_mul_f32 v[58:59], v[58:59], v[114:115]
	v_pk_mul_f32 v[54:55], v[54:55], v[118:119]
	v_pk_mul_f32 v[50:51], v[50:51], v[122:123]
	v_pk_mul_f32 v[60:61], v[60:61], v[10:11]
	v_pk_mul_f32 v[56:57], v[56:57], v[112:113]
	v_pk_mul_f32 v[52:53], v[52:53], v[116:117]
	v_pk_mul_f32 v[48:49], v[48:49], v[120:121]
	v_pk_mul_f32 v[78:79], v[78:79], v[12:13]
	v_pk_mul_f32 v[74:75], v[74:75], v[114:115]
	v_pk_mul_f32 v[70:71], v[70:71], v[118:119]
	v_pk_mul_f32 v[66:67], v[66:67], v[122:123]
	v_pk_mul_f32 v[76:77], v[76:77], v[10:11]
	v_pk_mul_f32 v[72:73], v[72:73], v[112:113]
	v_pk_mul_f32 v[68:69], v[68:69], v[116:117]
	v_pk_mul_f32 v[64:65], v[64:65], v[120:121]
	v_pk_mul_f32 v[46:47], v[46:47], v[12:13]
	v_pk_mul_f32 v[42:43], v[42:43], v[114:115]
	v_pk_mul_f32 v[38:39], v[38:39], v[118:119]
	v_pk_mul_f32 v[34:35], v[34:35], v[122:123]
	v_pk_mul_f32 v[44:45], v[44:45], v[10:11]
	v_pk_mul_f32 v[40:41], v[40:41], v[112:113]
	v_pk_mul_f32 v[36:37], v[36:37], v[116:117]
	v_pk_mul_f32 v[32:33], v[32:33], v[120:121]
	s_branch .LBB0_1181
